# cross-attention softmax block: V-fragment reads issued before the row-max chain (fills the MFMA->VALU wait), row-max half exchange by v_permlane32_swap
# baseline (speedup 1.0000x reference)
; template <bool DIFF> ...
;     ...
; #pragma unroll 1
;             for (int kq = 0; kq < NKS; kq += 4) {
;                 bf16x8 ka0[4], ka1[4], qq[4];
; #pragma unroll
;                 for (int j = 0; j < 4; ++j) {
;                     if (DIFF) { const int ko = 256 * l32 + 16 * (((c << 3) + 2 * j + hi) ^ (((l32 & 3) << 2) | ((l32 >> 2) & 3)));
;                         ka0[j] = *(LAS const bf16x8*)(kb + ko); ka1[j] = *(LAS const bf16x8*)(kb + 8192 + ko); }
;                     else { ka0[j] = *(LAS const bf16x8*)(ka + (kq + j) * 32); ka1[j] = *(LAS const bf16x8*)(ka + 32 * KSTR + (kq + j) * 32); }
;                     qq[j] = DIFF ? qf[DIFF ? j : 0] : *(LAS const bf16x8*)(qa + (kq + j) * 32); }
;                 __builtin_amdgcn_sched_barrier(0);
; #pragma unroll
;                 for (int j = 0; j < 4; ++j) { s0 = __builtin_amdgcn_mfma_f32_32x32x16_bf16(ka0[j], qq[j], s0, 0, 0, 0); s1 = __builtin_amdgcn_mfma_f32_32x32x16_bf16(ka1[j], qq[j], s1, 0, 0, 0); }
;             }
;             float c0 = 0.f, c1 = 0.f;
;             if (DIFF) {
;                 c0 = sl2 * (float)(64 * kt - wrow); c1 = sl2 * (float)(64 * kt + 32 - wrow);
;                 if (64 * kt + 64 > wrow) {
;                     asm volatile("" ::: "memory");
;                     const int irel = wrow + l32 - 64 * kt - hi * 4;
; #pragma unroll
;                     for (int r = 0; r < 16; ++r) { const int cr = (r >> 2) * 8 + (r & 3); if (cr > irel) s0[r] = -INFINITY; if (cr + 32 > irel) s1[r] = -INFINITY; }
;                 }
;             }
;             LAS const unsigned char* va = vb + (hi * 4 + ((lane & 15) >> 2)) * VSTR + (DIFF ? 0 : c * 256) + (((lane >> 4) & 1) * 16 + 4 * (lane & 3)) * 2;
;             bf16x8 fa[4], fb[4];
;             const int vq = (lane & 15) >> 2, vp = lane & 3, vg1 = (lane >> 4) & 1;
;             const int vs0 = 256 * (hi * 4 + vq) + 16 * ((2 * vg1 + (vp >> 1)) ^ hi) + 8 * (vp & 1), vs1 = 256 * (hi * 4 + 8 + vq) + 16 * ((2 * vg1 + (vp >> 1)) ^ (hi + 2)) + 8 * (vp & 1);
;     ...
;             float mx0 = s0[0], mx1 = s1[0];
; #pragma unroll
;             for (int r = 1; r < 16; r += 2) { mx0 = fmaxf(fmaxf(mx0, s0[r]), s0[r + 1 < 16 ? r + 1 : r]); mx1 = fmaxf(fmaxf(mx1, s1[r]), s1[r + 1 < 16 ? r + 1 : r]); }
;             float mx = fmaxf(__builtin_fmaf(mx0, sc2, c0), __builtin_fmaf(mx1, sc2, c1));
;             mx = fmaxf(mx, __shfl_xor(mx, 32));
.LBB0_256:
	v_add_u32_e32 v176, v146, v200
	v_add_u32_e32 v147, v0, v200
	v_add_u32_e32 v164, 0x11400, v176
	v_add_u32_e32 v168, 0x11420, v176
	ds_read_b128 v[148:151], v147
	ds_read_b128 v[152:155], v147 offset:32
	ds_read_b128 v[156:159], v147 offset:16896
	ds_read_b128 v[160:163], v147 offset:16928
	ds_read_b128 v[164:167], v164
	ds_read_b128 v[168:171], v168
	ds_read_b128 v[172:175], v147 offset:64
	ds_read_b128 v[210:213], v147 offset:96
	ds_read_b128 v[214:217], v147 offset:16960
	ds_read_b128 v[218:221], v147 offset:16992
	v_add_u32_e32 v177, 0x11440, v176
	v_add_u32_e32 v147, 0x11460, v176
	ds_read_b128 v[222:225], v177
	ds_read_b128 v[226:229], v147
	s_waitcnt lgkmcnt(7)
	v_mfma_f32_32x32x16_bf16 v[98:113], v[148:151], v[164:167], v[98:113]
	s_add_i32 s18, s18, 4
	v_add_u32_e32 v146, 0x80, v146
	v_add_u32_e32 v0, 0x80, v0
	s_cmp_gt_u32 s18, 11
	v_mfma_f32_32x32x16_bf16 v[82:97], v[156:159], v[164:167], v[82:97]
	s_waitcnt lgkmcnt(6)
	v_mfma_f32_32x32x16_bf16 v[98:113], v[152:155], v[168:171], v[98:113]
	v_mfma_f32_32x32x16_bf16 v[82:97], v[160:163], v[168:171], v[82:97]
	s_waitcnt lgkmcnt(1)
	v_mfma_f32_32x32x16_bf16 v[98:113], v[172:175], v[222:225], v[98:113]
	v_mfma_f32_32x32x16_bf16 v[82:97], v[214:217], v[222:225], v[82:97]
	s_waitcnt lgkmcnt(0)
	v_mfma_f32_32x32x16_bf16 v[98:113], v[210:213], v[226:229], v[98:113]
	v_mfma_f32_32x32x16_bf16 v[82:97], v[218:221], v[226:229], v[82:97]
	s_cbranch_scc0 .LBB0_256
	ds_read_b64_tr_b16 v[162:163], v204 offset:33792
	ds_read_b64_tr_b16 v[164:165], v204 offset:38400
	ds_read_b64_tr_b16 v[148:149], v204 offset:38464
	ds_read_b64_tr_b16 v[146:147], v204 offset:33856
	ds_read_b64_tr_b16 v[166:167], v204 offset:43008
	ds_read_b64_tr_b16 v[168:169], v204 offset:47616
	ds_read_b64_tr_b16 v[152:153], v204 offset:47680
	ds_read_b64_tr_b16 v[150:151], v204 offset:43072
	ds_read_b64_tr_b16 v[170:171], v204 offset:52224
	ds_read_b64_tr_b16 v[172:173], v204 offset:56832
	ds_read_b64_tr_b16 v[156:157], v204 offset:56896
	ds_read_b64_tr_b16 v[154:155], v204 offset:52288
	ds_read_b64_tr_b16 v[174:175], v204 offset:61440
	ds_read_b64_tr_b16 v[176:177], v205 offset:32256
	ds_read_b64_tr_b16 v[160:161], v205 offset:32320
	ds_read_b64_tr_b16 v[158:159], v204 offset:61504
	v_max_f32_e32 v0, v99, v99
	v_max_f32_e32 v236, v98, v98
	v_max_f32_e32 v0, v236, v0
	v_max_f32_e32 v236, v83, v83
	v_max_f32_e32 v237, v82, v82
	v_max_f32_e32 v236, v237, v236
	v_max3_f32 v0, v0, v100, v101
	v_max3_f32 v236, v236, v84, v85
	v_max3_f32 v0, v0, v102, v103
	v_max3_f32 v236, v236, v86, v87
	v_max3_f32 v0, v0, v104, v105
	v_max3_f32 v236, v236, v88, v89
	v_max3_f32 v0, v0, v106, v107
	v_max3_f32 v236, v236, v90, v91
	v_max3_f32 v0, v0, v108, v109
	v_max3_f32 v236, v236, v92, v93
	v_max3_f32 v0, v0, v110, v111
	v_max3_f32 v236, v236, v94, v95
	v_max3_f32 v0, v0, v112, v113
	v_max3_f32 v236, v236, v96, v97
	v_fma_f32 v0, v0, s44, 0
	v_fma_f32 v236, v236, s44, 0
	v_max_f32_e32 v0, v0, v236
	v_mov_b32_e32 v209, v0
	v_mov_b32_e32 v236, v0
	s_nop 1
	v_permlane32_swap_b32_e32 v209, v236
	s_nop 1
	v_max_f32_e32 v0, v209, v236
	s_waitcnt lgkmcnt(14)
	v_cmp_gt_f32_e32 vcc, v0, v208
	s_cbranch_vccz .LBB0_252
	v_max_f32_e32 v0, v0, v0
	v_max_f32_e32 v209, v208, v208
	v_max_f32_e32 v209, v209, v0
	v_sub_f32_e32 v0, v208, v209
	v_exp_f32_e32 v0, v0
	v_mov_b32_e32 v208, v209
	v_pk_mul_f32 v[64:65], v[64:65], v[0:1] op_sel_hi:[1,0]
	v_pk_mul_f32 v[62:63], v[62:63], v[0:1] op_sel_hi:[1,0]
	v_pk_mul_f32 v[60:61], v[60:61], v[0:1] op_sel_hi:[1,0]
	v_pk_mul_f32 v[58:59], v[58:59], v[0:1] op_sel_hi:[1,0]
	v_pk_mul_f32 v[56:57], v[56:57], v[0:1] op_sel_hi:[1,0]
	v_pk_mul_f32 v[54:55], v[54:55], v[0:1] op_sel_hi:[1,0]
	v_pk_mul_f32 v[52:53], v[52:53], v[0:1] op_sel_hi:[1,0]
	v_pk_mul_f32 v[50:51], v[50:51], v[0:1] op_sel_hi:[1,0]
	v_pk_mul_f32 v[48:49], v[48:49], v[0:1] op_sel_hi:[1,0]
	v_pk_mul_f32 v[46:47], v[46:47], v[0:1] op_sel_hi:[1,0]
	v_pk_mul_f32 v[44:45], v[44:45], v[0:1] op_sel_hi:[1,0]
	v_pk_mul_f32 v[42:43], v[42:43], v[0:1] op_sel_hi:[1,0]
	v_pk_mul_f32 v[40:41], v[40:41], v[0:1] op_sel_hi:[1,0]
	v_pk_mul_f32 v[38:39], v[38:39], v[0:1] op_sel_hi:[1,0]
	v_pk_mul_f32 v[36:37], v[36:37], v[0:1] op_sel_hi:[1,0]
	v_pk_mul_f32 v[34:35], v[34:35], v[0:1] op_sel_hi:[1,0]
	v_pk_mul_f32 v[32:33], v[32:33], v[0:1] op_sel_hi:[1,0]
	v_pk_mul_f32 v[30:31], v[30:31], v[0:1] op_sel_hi:[1,0]
	v_pk_mul_f32 v[28:29], v[28:29], v[0:1] op_sel_hi:[1,0]
	v_pk_mul_f32 v[26:27], v[26:27], v[0:1] op_sel_hi:[1,0]
	v_pk_mul_f32 v[24:25], v[24:25], v[0:1] op_sel_hi:[1,0]
	v_pk_mul_f32 v[22:23], v[22:23], v[0:1] op_sel_hi:[1,0]
	v_pk_mul_f32 v[20:21], v[20:21], v[0:1] op_sel_hi:[1,0]
	v_pk_mul_f32 v[18:19], v[18:19], v[0:1] op_sel_hi:[1,0]
	v_pk_mul_f32 v[16:17], v[16:17], v[0:1] op_sel_hi:[1,0]
	v_pk_mul_f32 v[14:15], v[14:15], v[0:1] op_sel_hi:[1,0]
	v_pk_mul_f32 v[12:13], v[12:13], v[0:1] op_sel_hi:[1,0]
	v_pk_mul_f32 v[10:11], v[10:11], v[0:1] op_sel_hi:[1,0]
	v_pk_mul_f32 v[8:9], v[8:9], v[0:1] op_sel_hi:[1,0]
	v_pk_mul_f32 v[6:7], v[6:7], v[0:1] op_sel_hi:[1,0]
	v_pk_mul_f32 v[4:5], v[4:5], v[0:1] op_sel_hi:[1,0]
	v_pk_mul_f32 v[2:3], v[2:3], v[0:1] op_sel_hi:[1,0]
	v_mul_f32_e32 v203, v203, v0
	s_branch .LBB0_252
